# stack3: stack2 + gMLP u/MIX tiles staged through wave-private LDS for full-line global accesses + latent attention O tile stored as whole lines via LDS
# speedup vs baseline: 1.0225x; 1.0061x over previous
; DI void attn_unit(const Params& p, int l, int b, int kvh, int qb, bool isctx, ldsp_t smem) {
;     ...
;     for (int t = 0; t < ntile; t += 2) {
;         ATT_STEP(t, sA, sB);
;         ATT_STEP(t + 1, sB, sA);
;     }
.LBB0_164:
	s_add_i32 s10, s9, 4
	s_min_u32 s10, s10, 0x43
	s_lshl_b32 s98, s10, 13
	v_lshl_add_u64 v[80:81], v[146:147], 0, s[98:99]
	s_waitcnt lgkmcnt(0)
	s_barrier
	global_load_dwordx4 v[132:135], v[80:81], off
	global_load_dwordx4 v[128:131], v[150:151], off
	v_add_u32_e32 v171, v192, v167
	v_add_u32_e32 v172, v192, v168
	v_add_u32_e32 v142, v192, v169
	v_add_u32_e32 v143, v192, v170
	ds_read_b128 v[80:83], v171 offset:8192
	ds_read_b128 v[138:141], v171 offset:12288
	ds_read_b128 v[152:155], v172 offset:8192
	ds_read_b128 v[156:159], v172 offset:12288
	ds_read_b128 v[160:163], v142 offset:8192
	ds_read_b128 v[174:177], v142 offset:12288
	ds_read_b128 v[178:181], v143 offset:8192
	ds_read_b128 v[182:185], v143 offset:12288
	ds_read_b128 v[186:189], v171 offset:16384
	ds_read_b128 v[194:197], v171 offset:20480
	ds_read_b128 v[198:201], v172 offset:16384
	ds_read_b128 v[204:207], v172 offset:20480
	s_add_i32 s9, s9, 2
	s_waitcnt lgkmcnt(11)
	v_mfma_f32_32x32x16_bf16 v[96:111], v[80:83], v[112:115], v[32:47]
	v_exp_f32_e32 v64, v64
	v_exp_f32_e32 v65, v65
	v_exp_f32_e32 v66, v66
	v_exp_f32_e32 v67, v67
	v_exp_f32_e32 v68, v68
	v_exp_f32_e32 v69, v69
	v_exp_f32_e32 v74, v74
	s_waitcnt lgkmcnt(10)
	v_mfma_f32_32x32x16_bf16 v[80:95], v[138:141], v[112:115], v[32:47]
	v_exp_f32_e32 v138, v70
	v_exp_f32_e32 v139, v71
	v_exp_f32_e32 v140, v72
	v_exp_f32_e32 v141, v73
	v_exp_f32_e32 v75, v75
	v_exp_f32_e32 v70, v76
	v_exp_f32_e32 v71, v77
	s_waitcnt lgkmcnt(9)
	v_mfma_f32_32x32x16_bf16 v[96:111], v[152:155], v[116:119], v[96:111]
	v_exp_f32_e32 v152, v54
	v_exp_f32_e32 v153, v55
	v_cvt_pk_bf16_f32 v54, v68, v69
	v_cvt_pk_bf16_f32 v55, v138, v139
	v_exp_f32_e32 v72, v78
	v_exp_f32_e32 v73, v79
	v_exp_f32_e32 v48, v48
	s_waitcnt lgkmcnt(8)
	v_mfma_f32_32x32x16_bf16 v[80:95], v[156:159], v[116:119], v[80:95]
	v_exp_f32_e32 v158, v52
	v_exp_f32_e32 v159, v53
	v_cvt_pk_bf16_f32 v52, v64, v65
	v_cvt_pk_bf16_f32 v53, v66, v67
	v_exp_f32_e32 v49, v49
	v_exp_f32_e32 v50, v50
	v_exp_f32_e32 v51, v51
	s_waitcnt lgkmcnt(3)
	v_mfma_f32_32x32x16_bf16 v[16:31], v[186:189], v[52:55], v[16:31]
	v_exp_f32_e32 v154, v56
	v_exp_f32_e32 v155, v57
	v_exp_f32_e32 v156, v58
	v_exp_f32_e32 v157, v59
	s_min_u32 s11, s9, 64
	s_lshl_b32 s98, s11, 13
	v_pk_add_f32 v[56:57], v[136:137], v[64:65]
	s_waitcnt lgkmcnt(2)
	v_mfma_f32_32x32x16_bf16 v[0:15], v[194:197], v[52:55], v[0:15]
	v_cvt_pk_bf16_f32 v52, v140, v141
	v_cvt_pk_bf16_f32 v53, v74, v75
	v_cvt_pk_bf16_f32 v54, v70, v71
	v_cvt_pk_bf16_f32 v55, v72, v73
	v_add_f32_e64 v56, v66, v56
	v_add_f32_e64 v57, v67, v57
	v_pk_add_f32 v[56:57], v[68:69], v[56:57]
	v_mfma_f32_32x32x16_bf16 v[96:111], v[160:163], v[120:123], v[96:111]
	v_exp_f32_e32 v160, v60
	v_exp_f32_e32 v161, v61
	v_exp_f32_e32 v162, v62
	v_exp_f32_e32 v163, v63
	v_pk_add_f32 v[56:57], v[138:139], v[56:57]
	s_nop 0
	v_pk_add_f32 v[56:57], v[140:141], v[56:57]
	v_mfma_f32_32x32x16_bf16 v[80:95], v[174:177], v[120:123], v[80:95]
	v_add_f32_e64 v56, v74, v56
	v_add_f32_e64 v57, v75, v57
	v_add_f32_e64 v56, v70, v56
	v_add_f32_e64 v57, v71, v57
	v_add_f32_e64 v56, v72, v56
	v_add_f32_e64 v57, v73, v57
	s_waitcnt lgkmcnt(1)
	v_mfma_f32_32x32x16_bf16 v[16:31], v[198:201], v[52:55], v[16:31]
	s_waitcnt lgkmcnt(0)
	v_mfma_f32_32x32x16_bf16 v[0:15], v[204:207], v[52:55], v[0:15]
	v_cvt_pk_bf16_f32 v52, v48, v49
	v_cvt_pk_bf16_f32 v53, v50, v51
	v_cvt_pk_bf16_f32 v54, v158, v159
	v_cvt_pk_bf16_f32 v55, v152, v153
	v_add_f32_e64 v48, v48, v56
	v_add_f32_e64 v49, v49, v57
	v_pk_add_f32 v[190:191], v[50:51], v[48:49]
	v_mfma_f32_32x32x16_bf16 v[96:111], v[178:181], v[124:127], v[96:111]
	v_mfma_f32_32x32x16_bf16 v[80:95], v[182:185], v[124:127], v[80:95]
	ds_read_b128 v[174:177], v142 offset:16384
	ds_read_b128 v[178:181], v142 offset:20480
	ds_read_b128 v[182:185], v143 offset:16384
	ds_read_b128 v[210:213], v143 offset:20480
	s_waitcnt vmcnt(1)
	ds_write_b128 v145, v[132:135]
	s_waitcnt vmcnt(0)
	ds_write_b128 v145, v[128:131] offset:24576
	s_waitcnt lgkmcnt(0)
	s_barrier
	v_mfma_f32_32x32x16_bf16 v[16:31], v[174:177], v[52:55], v[16:31]
	v_mfma_f32_32x32x16_bf16 v[0:15], v[178:181], v[52:55], v[0:15]
	v_cvt_pk_bf16_f32 v52, v154, v155
	v_cvt_pk_bf16_f32 v53, v156, v157
	v_cvt_pk_bf16_f32 v54, v160, v161
	v_cvt_pk_bf16_f32 v55, v162, v163
	s_nop 1
	v_mfma_f32_32x32x16_bf16 v[16:31], v[182:185], v[52:55], v[16:31]
	v_mfma_f32_32x32x16_bf16 v[0:15], v[210:213], v[52:55], v[0:15]
	v_lshl_add_u64 v[52:53], v[146:147], 0, s[98:99]
	v_add_co_u32_e32 v52, vcc, s28, v52
	s_lshl_b32 s98, s10, 7
	s_nop 0
	v_addc_co_u32_e32 v53, vcc, 0, v53, vcc
	global_load_dwordx4 v[128:131], v[52:53], off
	v_lshl_add_u64 v[52:53], v[148:149], 0, s[98:99]
	global_load_dwordx4 v[132:135], v[52:53], off
	ds_read_b128 v[52:55], v171
	ds_read_b128 v[174:177], v172
	ds_read_b128 v[178:181], v142
	ds_read_b128 v[182:185], v143
	ds_read_b128 v[186:189], v171 offset:4096
	ds_read_b128 v[194:197], v172 offset:4096
	ds_read_b128 v[198:201], v142 offset:4096
	ds_read_b128 v[204:207], v143 offset:4096
	ds_read_b128 v[210:213], v171 offset:24576
	ds_read_b128 v[214:217], v171 offset:28672
	ds_read_b128 v[218:221], v172 offset:24576
	ds_read_b128 v[222:225], v172 offset:28672
	v_exp_f32_e32 v96, v96
	v_exp_f32_e32 v97, v97
	v_exp_f32_e32 v98, v98
	v_exp_f32_e32 v99, v99
	v_exp_f32_e32 v100, v100
	v_exp_f32_e32 v101, v101
	v_exp_f32_e32 v102, v102
	v_exp_f32_e32 v103, v103
	v_pk_add_f32 v[158:159], v[158:159], v[190:191]
	s_waitcnt lgkmcnt(11)
; DI void attn_unit(const Params& p, int l, int b, int kvh, int qb, bool isctx, ldsp_t smem) {
;     ...
;     for (int t = 0; t < ntile; t += 2) {
;         ATT_STEP(t, sA, sB);
;         ATT_STEP(t + 1, sB, sA);
	v_mfma_f32_32x32x16_bf16 v[64:79], v[52:55], v[112:115], v[32:47]
	v_add_f32_e64 v152, v152, v158
	v_add_f32_e64 v153, v153, v159
	v_exp_f32_e32 v104, v104
	v_pk_add_f32 v[152:153], v[154:155], v[152:153]
	v_exp_f32_e32 v154, v80
	v_pk_add_f32 v[152:153], v[156:157], v[152:153]
	v_exp_f32_e32 v155, v81
	v_exp_f32_e32 v156, v82
	v_exp_f32_e32 v157, v83
	v_cvt_pk_bf16_f32 v80, v96, v97
	v_cvt_pk_bf16_f32 v81, v98, v99
	v_cvt_pk_bf16_f32 v82, v100, v101
	v_cvt_pk_bf16_f32 v83, v102, v103
	s_waitcnt lgkmcnt(7)
	v_mfma_f32_32x32x16_bf16 v[48:63], v[186:189], v[112:115], v[32:47]
	v_exp_f32_e32 v105, v105
	v_exp_f32_e32 v106, v106
	v_exp_f32_e32 v107, v107
	v_exp_f32_e32 v108, v108
	v_exp_f32_e32 v109, v109
	v_exp_f32_e32 v110, v110
	v_exp_f32_e32 v111, v111
	s_waitcnt lgkmcnt(3)
	v_mfma_f32_32x32x16_bf16 v[16:31], v[210:213], v[80:83], v[16:31]
	v_exp_f32_e32 v84, v84
	v_exp_f32_e32 v85, v85
	v_exp_f32_e32 v86, v86
	v_exp_f32_e32 v87, v87
	v_pk_add_f32 v[152:153], v[160:161], v[152:153]
	v_exp_f32_e32 v88, v88
	v_pk_add_f32 v[152:153], v[162:163], v[152:153]
	s_waitcnt lgkmcnt(2)
	v_mfma_f32_32x32x16_bf16 v[0:15], v[214:217], v[80:83], v[0:15]
	v_cvt_pk_bf16_f32 v80, v104, v105
	v_cvt_pk_bf16_f32 v81, v106, v107
	v_cvt_pk_bf16_f32 v82, v108, v109
	v_cvt_pk_bf16_f32 v83, v110, v111
	v_add_f32_e64 v152, v152, v96
	v_add_f32_e64 v153, v153, v97
	v_exp_f32_e32 v89, v89
	v_exp_f32_e32 v90, v90
	v_mfma_f32_32x32x16_bf16 v[64:79], v[174:177], v[116:119], v[64:79]
	v_exp_f32_e32 v91, v91
	v_exp_f32_e32 v92, v92
	v_exp_f32_e32 v93, v93
	v_exp_f32_e32 v94, v94
	v_exp_f32_e32 v95, v95
	v_pk_add_f32 v[152:153], v[98:99], v[152:153]
	v_lshl_add_u64 v[150:151], v[150:151], 0, s[96:97]
	s_waitcnt lgkmcnt(1)
	v_mfma_f32_32x32x16_bf16 v[16:31], v[218:221], v[80:83], v[16:31]
	v_add_f32_e64 v152, v100, v152
	v_add_f32_e64 v153, v101, v153
	s_cmpk_lt_u32 s9, 0x42
	v_add_f32_e64 v152, v102, v152
	v_add_f32_e64 v153, v103, v153
	v_pk_add_f32 v[152:153], v[104:105], v[152:153]
	s_waitcnt lgkmcnt(0)
	v_mfma_f32_32x32x16_bf16 v[0:15], v[222:225], v[80:83], v[0:15]
	v_cvt_pk_bf16_f32 v80, v154, v155
	v_cvt_pk_bf16_f32 v81, v156, v157
	v_cvt_pk_bf16_f32 v82, v84, v85
	v_cvt_pk_bf16_f32 v83, v86, v87
	v_mfma_f32_32x32x16_bf16 v[48:63], v[194:197], v[116:119], v[48:63]
	v_mfma_f32_32x32x16_bf16 v[64:79], v[178:181], v[120:123], v[64:79]
	ds_read_b128 v[172:175], v142 offset:24576
	ds_read_b128 v[176:179], v142 offset:28672
	ds_read_b128 v[136:139], v143 offset:24576
	ds_read_b128 v[140:143], v143 offset:28672
	s_waitcnt vmcnt(1)
	ds_write_b128 v145, v[128:131] offset:8192
	s_waitcnt vmcnt(0)
	ds_write_b128 v145, v[132:135] offset:16384
	s_waitcnt lgkmcnt(5)
	v_mfma_f32_32x32x16_bf16 v[16:31], v[172:175], v[80:83], v[16:31]
	s_waitcnt lgkmcnt(4)
	v_mfma_f32_32x32x16_bf16 v[0:15], v[176:179], v[80:83], v[0:15]
	v_cvt_pk_bf16_f32 v80, v88, v89
	v_cvt_pk_bf16_f32 v81, v90, v91
	v_cvt_pk_bf16_f32 v82, v92, v93
	v_cvt_pk_bf16_f32 v83, v94, v95
	v_mfma_f32_32x32x16_bf16 v[48:63], v[198:201], v[120:123], v[48:63]
	s_waitcnt lgkmcnt(3)
	v_mfma_f32_32x32x16_bf16 v[16:31], v[136:139], v[80:83], v[16:31]
	s_waitcnt lgkmcnt(2)
	v_mfma_f32_32x32x16_bf16 v[0:15], v[140:143], v[80:83], v[0:15]
	v_add_f32_e64 v80, v106, v152
	v_add_f32_e64 v81, v107, v153
	v_add_f32_e64 v80, v108, v80
	v_add_f32_e64 v81, v109, v81
	v_add_f32_e64 v80, v110, v80
	v_add_f32_e64 v81, v111, v81
	v_pk_add_f32 v[80:81], v[154:155], v[80:81]
	v_mfma_f32_32x32x16_bf16 v[64:79], v[182:185], v[124:127], v[64:79]
	v_add_f32_e64 v80, v156, v80
	v_add_f32_e64 v81, v157, v81
	v_add_f32_e64 v80, v84, v80
	v_add_f32_e64 v81, v85, v81
	v_add_f32_e64 v80, v86, v80
	v_add_f32_e64 v81, v87, v81
	v_pk_add_f32 v[80:81], v[88:89], v[80:81]
	v_mfma_f32_32x32x16_bf16 v[48:63], v[204:207], v[124:127], v[48:63]
	v_add_f32_e64 v80, v90, v80
	v_add_f32_e64 v81, v91, v81
	v_add_f32_e64 v80, v92, v80
	v_add_f32_e64 v81, v93, v81
	v_add_f32_e64 v136, v94, v80
	v_add_f32_e64 v137, v95, v81
	s_cbranch_scc1 .LBB0_164
; DI unsigned pk2(float a, float b) { f32x2 v = {a, b}; bf2_t r = __builtin_convertvector(v, bf2_t); return __builtin_bit_cast(unsigned, r); }
; DI void attn_unit(const Params& p, int l, int b, int kvh, int qb, bool isctx, ldsp_t smem) {
;     ...
;     const float lrun = rs0 + rs1;
;     const float ltot = lrun + __shfl_xor(lrun, 32);
;     const float inv = 1.f / ltot;
; #pragma unroll
;     for (int dt = 0; dt < 2; ++dt)
; #pragma unroll
;         for (int g4 = 0; g4 < 4; ++g4) {
;             u32x2 w; w[0] = pk2(o[dt][4 * g4 + 0] * inv, o[dt][4 * g4 + 1] * inv); w[1] = pk2(o[dt][4 * g4 + 2] * inv, o[dt][4 * g4 + 3] * inv);
;             *(u32x2*)(Op + (size_t)r * DM + dt * 32 + 8 * g4 + 4 * hh) = w;
;         }
;     __syncthreads();
	v_lshrrev_b32_e32 v42, 6, v252
	v_mul_u32_u24_e32 v42, 0x1200, v42
	v_add_u32_e32 v42, 0x8000, v42
	v_and_b32_e32 v43, 31, v252
	v_mul_u32_u24_e32 v43, 0x90, v43
	v_bfe_u32 v40, v252, 5, 1
	v_lshl_add_u32 v40, v40, 3, v43
	v_add_u32_e32 v40, v42, v40
	v_bfe_u32 v43, v252, 3, 3
	v_mul_u32_u24_e32 v43, 0x90, v43
	v_and_b32_e32 v41, 7, v252
	v_lshl_add_u32 v41, v41, 4, v43
	v_add_u32_e32 v41, v42, v41
	v_lshl_add_u32 v32, s7, 12, v144
	v_ashrrev_i32_e32 v33, 31, v32
	v_lshlrev_b64 v[32:33], 11, v[32:33]
	v_lshlrev_b32_e32 v34, 6, v166
	v_lshl_add_u64 v[32:33], s[18:19], 0, v[32:33]
	v_ashrrev_i32_e32 v35, 31, v34
	v_cmp_lt_i32_e32 vcc, v209, v203
	v_lshl_add_u64 v[32:33], v[34:35], 1, v[32:33]
	v_add_f32_e32 v34, v137, v136
	v_cndmask_b32_e32 v35, v202, v209, vcc
	v_lshlrev_b32_e32 v35, 2, v35
	ds_bpermute_b32 v35, v35, v34
	v_bfe_u32 v192, v252, 3, 3
	v_lshlrev_b32_e32 v192, 11, v192
	v_lshl_add_u64 v[32:33], v[32:33], 0, v[192:193]
	v_and_b32_e32 v192, 7, v252
	v_lshlrev_b32_e32 v192, 4, v192
	v_lshl_add_u64 v[32:33], v[32:33], 0, v[192:193]
	s_waitcnt lgkmcnt(0)
	v_add_f32_e32 v34, v34, v35
	v_div_scale_f32 v35, s[10:11], v34, v34, 1.0
	v_rcp_f32_e32 v36, v35
	s_nop 0
	v_fma_f32 v37, -v35, v36, 1.0
	v_fmac_f32_e32 v36, v37, v36
	v_div_scale_f32 v37, vcc, 1.0, v34, 1.0
	v_mul_f32_e32 v38, v37, v36
	v_fma_f32 v39, -v35, v38, v37
	v_fmac_f32_e32 v38, v39, v36
	v_fma_f32 v35, -v35, v38, v37
	v_div_fmas_f32 v35, v35, v36, v38
	v_div_fixup_f32 v34, v35, v34, 1.0
	v_pk_mul_f32 v[16:17], v[16:17], v[34:35] op_sel_hi:[1,0]
	v_pk_mul_f32 v[18:19], v[18:19], v[34:35] op_sel_hi:[1,0]
	v_pk_mul_f32 v[0:1], v[0:1], v[34:35] op_sel_hi:[1,0]
	v_pk_mul_f32 v[2:3], v[2:3], v[34:35] op_sel_hi:[1,0]
	v_cvt_pk_bf16_f32 v16, v16, v17
	v_cvt_pk_bf16_f32 v17, v18, v19
	v_cvt_pk_bf16_f32 v0, v0, v1
	v_cvt_pk_bf16_f32 v1, v2, v3
	ds_write_b64 v40, v[16:17]
	v_pk_mul_f32 v[16:17], v[20:21], v[34:35] op_sel_hi:[1,0]
	v_pk_mul_f32 v[18:19], v[22:23], v[34:35] op_sel_hi:[1,0]
	ds_write_b64 v40, v[0:1] offset:64
	v_pk_mul_f32 v[0:1], v[4:5], v[34:35] op_sel_hi:[1,0]
	v_pk_mul_f32 v[2:3], v[6:7], v[34:35] op_sel_hi:[1,0]
	v_cvt_pk_bf16_f32 v16, v16, v17
	v_cvt_pk_bf16_f32 v17, v18, v19
	v_cvt_pk_bf16_f32 v0, v0, v1
	v_cvt_pk_bf16_f32 v1, v2, v3
	ds_write_b64 v40, v[16:17] offset:16
	v_pk_mul_f32 v[16:17], v[24:25], v[34:35] op_sel_hi:[1,0]
	v_pk_mul_f32 v[18:19], v[26:27], v[34:35] op_sel_hi:[1,0]
	ds_write_b64 v40, v[0:1] offset:80
	v_pk_mul_f32 v[0:1], v[8:9], v[34:35] op_sel_hi:[1,0]
	v_pk_mul_f32 v[2:3], v[10:11], v[34:35] op_sel_hi:[1,0]
	v_cvt_pk_bf16_f32 v16, v16, v17
	v_cvt_pk_bf16_f32 v17, v18, v19
	v_cvt_pk_bf16_f32 v0, v0, v1
	v_cvt_pk_bf16_f32 v1, v2, v3
	ds_write_b64 v40, v[16:17] offset:32
	v_pk_mul_f32 v[16:17], v[28:29], v[34:35] op_sel_hi:[1,0]
	v_pk_mul_f32 v[18:19], v[30:31], v[34:35] op_sel_hi:[1,0]
	ds_write_b64 v40, v[0:1] offset:96
	v_pk_mul_f32 v[0:1], v[12:13], v[34:35] op_sel_hi:[1,0]
	v_pk_mul_f32 v[2:3], v[14:15], v[34:35] op_sel_hi:[1,0]
	v_cvt_pk_bf16_f32 v16, v16, v17
	v_cvt_pk_bf16_f32 v17, v18, v19
	v_cvt_pk_bf16_f32 v0, v0, v1
	v_cvt_pk_bf16_f32 v1, v2, v3
	ds_write_b64 v40, v[16:17] offset:48
	ds_write_b64 v40, v[0:1] offset:112
	ds_read_b128 v[44:47], v41
	ds_read_b128 v[48:51], v41 offset:1152
	ds_read_b128 v[52:55], v41 offset:2304
	ds_read_b128 v[56:59], v41 offset:3456
	v_mov_b32_e32 v192, 0x4000
	v_lshl_add_u64 v[60:61], v[32:33], 0, v[192:193]
	v_lshl_add_u64 v[62:63], v[60:61], 0, v[192:193]
	v_lshl_add_u64 v[64:65], v[62:63], 0, v[192:193]
	s_waitcnt lgkmcnt(0)
	global_store_dwordx4 v[32:33], v[44:47], off
	global_store_dwordx4 v[60:61], v[48:51], off
	global_store_dwordx4 v[62:63], v[52:55], off
	global_store_dwordx4 v[64:65], v[56:59], off
	s_barrier
	s_load_dword s7, s[88:89], 0x0
	s_waitcnt lgkmcnt(0)
	s_add_i32 s6, s7, s6
	s_cmpk_gt_i32 s6, 0x1ff
	s_cbranch_scc0 .LBB0_163

; DI void gmlp_unit(const Params& p, int l, int T, int g, ldsp_t smem) {
;     ...
;         const int q = tid >> 2, part = tid & 3;
;         const bf16_t* src = p.U + (size_t)(T * 128 + q) * 1024 + 512 + g * 128 + part * 32;
;         u32x4 raw[4];
; #pragma unroll
;         for (int i = 0; i < 4; ++i) raw[i] = *(const u32x4*)(src + i * 8);
;         float a = 0.f, b = 0.f;
; #pragma unroll
;         for (int i = 0; i < 4; ++i)
; #pragma unroll
;             for (int j = 0; j < 4; ++j) {
;                 const float lo = __uint_as_float(raw[i][j] << 16), hi = __uint_as_float(raw[i][j] & 0xffff0000u);
;                 a += lo + hi; b += lo * lo + hi * hi;
;             }
;         a += __shfl_xor(a, 1); a += __shfl_xor(a, 2);
;         b += __shfl_xor(b, 1); b += __shfl_xor(b, 2);
;         const float mean = a * (1.f / 128.f);
;         const float rstd = rsqrtf(fmaxf(b * (1.f / 128.f) - mean * mean, 0.f) + EPS);
;         const float* gn = p.gmlp_norm_g + l * 512 + g * 128 + part * 32;
;     ...
;     const float bs = p.b_spatial[(size_t)(l * 4 + g) * 128 + prow];
;     const int row = T * 128 + prow;
;     const bf16_t* up = p.U + (size_t)row * 1024 + g * 128 + fq * 4;
;     bf16_t* mp = p.MIX + (size_t)row * DM + 512 + g * 128 + fq * 4;
; #pragma unroll
;     for (int n = 0; n < 8; ++n) {
;         const u32x2 uu = *(const u32x2*)(up + n * 16);
;         const float u0 = __uint_as_float(uu[0] << 16), u1 = __uint_as_float(uu[0] & 0xffff0000u), u2 = __uint_as_float(uu[1] << 16), u3 = __uint_as_float(uu[1] & 0xffff0000u);
.LBB0_174:
	v_mov_b32_e32 v46, v252
	s_lshl_b32 s4, s11, 5
	s_and_b32 s31, s4, 0xffffff80
	v_ashrrev_i32_e32 v47, 2, v46
	v_add_u32_e32 v0, s31, v47
	v_ashrrev_i32_e32 v1, 31, v0
	s_and_b32 s34, s11, 3
	v_lshlrev_b64 v[0:1], 11, v[0:1]
	v_lshlrev_b32_e32 v2, 5, v46
	v_lshl_add_u64 v[0:1], s[16:17], 0, v[0:1]
	s_lshl_b32 s98, s34, 8
	v_and_b32_e32 v36, 0x60, v2
	v_lshl_add_u64 v[0:1], v[0:1], 0, s[98:99]
	v_lshlrev_b32_e32 v192, 1, v36
	s_waitcnt lgkmcnt(0)
	v_lshl_add_u64 v[4:5], v[0:1], 0, v[192:193]
	global_load_dwordx4 v[0:3], v[4:5], off offset:1072
	global_load_dwordx4 v[10:13], v[4:5], off offset:1056
	global_load_dwordx4 v[22:25], v[4:5], off offset:1040
	global_load_dwordx4 v[38:41], v[4:5], off offset:1024
	v_cmp_lt_i32_e32 vcc, v134, v203
	v_lshlrev_b32_e32 v64, 2, v36
	v_lshlrev_b32_e32 v57, 8, v36
	v_ashrrev_i32_e32 v36, 1, v46
	v_and_b32_e32 v58, -16, v36
	v_add_u32_e32 v36, v57, v58
	s_lshl_b32 s4, s34, 9
	s_add_u32 s4, s9, s4
	s_addc_u32 s5, s10, 0
	s_movk_i32 s35, 0x50
	s_brev_b32 s36, 60
	v_lshrrev_b32_e32 v44, 4, v46
	v_and_b32_e32 v45, 15, v46
	s_waitcnt vmcnt(3)
	v_lshlrev_b32_e32 v4, 16, v2
	v_and_b32_e32 v26, 0xffff0000, v2
	v_lshlrev_b32_e32 v5, 16, v3
	v_and_b32_e32 v27, 0xffff0000, v3
	v_mov_b32_e32 v28, v4
	v_mov_b32_e32 v29, v26
	v_mul_f32_e32 v2, v26, v26
	v_pk_fma_f32 v[30:31], v[28:29], v[28:29], v[2:3] op_sel_hi:[1,1,0]
	v_pk_add_f32 v[2:3], v[4:5], v[26:27]
	v_mov_b32_e32 v26, v5
	v_mul_f32_e32 v4, v27, v27
	v_pk_fma_f32 v[32:33], v[26:27], v[26:27], v[4:5] op_sel_hi:[1,1,0]
	v_cndmask_b32_e32 v4, v202, v134, vcc
	v_cmp_lt_i32_e32 vcc, v135, v203
	v_lshlrev_b32_e32 v62, 2, v4
	s_waitcnt vmcnt(0)
	v_and_b32_e32 v5, 0xffff0000, v38
	v_cndmask_b32_e32 v4, v202, v135, vcc
	v_lshlrev_b32_e32 v63, 2, v4
	v_lshlrev_b32_e32 v4, 1, v47
	v_and_b32_e32 v56, 14, v4
	v_or_b32_e32 v65, v36, v56
	v_xad_u32 v36, v58, 16, v57
	v_lshlrev_b32_e32 v34, 16, v38
	v_and_b32_e32 v4, s0, v38
	v_mov_b32_e32 v35, v5
	v_or_b32_e32 v66, v36, v56
	v_lshlrev_b32_e32 v36, 16, v39
	v_and_b32_e32 v37, 0xffff0000, v39
	v_pk_add_f32 v[42:43], v[34:35], v[4:5] op_sel_hi:[0,1]
	v_pk_mul_f32 v[38:39], v[36:37], v[36:37]
	v_pk_mul_f32 v[48:49], v[34:35], v[34:35]
	v_mov_b32_e32 v42, v38
	v_mov_b32_e32 v192, v39
	v_pk_add_f32 v[38:39], v[42:43], v[192:193]
	v_mov_b32_e32 v42, v48
	v_mov_b32_e32 v43, v36
	v_mov_b32_e32 v48, v49
	v_mov_b32_e32 v49, v37
	v_mov_b32_e32 v31, v2
	v_mov_b32_e32 v33, v3
	global_load_dwordx4 v[2:5], v64, s[4:5] offset:48
	global_load_dwordx4 v[6:9], v64, s[4:5] offset:32
	global_load_dwordx4 v[14:17], v64, s[4:5] offset:16
	global_load_dwordx4 v[18:21], v64, s[4:5]
	global_load_dwordx4 v[84:87], v64, s[4:5] offset:112
	global_load_dwordx4 v[88:91], v64, s[4:5] offset:96
	global_load_dwordx4 v[92:95], v64, s[4:5] offset:80
	global_load_dwordx4 v[96:99], v64, s[4:5] offset:64
	s_or_b32 s100, s34, s7
	s_lshl_b32 s100, s100, 7
	v_lshrrev_b32_e32 v116, 2, v252
	v_bfi_b32 v116, -16, v116, v252
	v_add_u32_e32 v117, s100, v116
	v_bfe_u32 v118, v252, 4, 2
	v_lshlrev_b32_e32 v119, 8, v117
	v_lshl_add_u32 v119, v118, 4, v119
	global_load_dwordx4 v[140:143], v119, s[64:65]
	global_load_dwordx4 v[144:147], v119, s[64:65] offset:64
	global_load_dwordx4 v[148:151], v119, s[64:65] offset:128
	global_load_dwordx4 v[152:155], v119, s[64:65] offset:192
	v_lshlrev_b32_e32 v117, 2, v117
	v_readlane_b32 s100, v253, 11
	v_readlane_b32 s101, v253, 12
	s_nop 4
	global_load_dword v156, v117, s[100:101]
	v_lshrrev_b32_e32 v120, 6, v252
	v_lshl_add_u32 v123, v120, 4, v118
	v_add_u32_e32 v123, s31, v123
	v_lshlrev_b32_e32 v123, 11, v123
	v_and_b32_e32 v128, 15, v252
	v_lshl_add_u32 v123, v128, 4, v123
	v_add_u32_e32 v124, s98, v123
	v_add_u32_e32 v125, 0x2000, v124
	v_add_u32_e32 v126, 0x4000, v124
	v_add_u32_e32 v127, 0x6000, v124
	global_load_dwordx4 v[168:171], v124, s[16:17]
	global_load_dwordx4 v[172:175], v125, s[16:17]
	global_load_dwordx4 v[176:179], v126, s[16:17]
	global_load_dwordx4 v[180:183], v127, s[16:17]
	v_mul_u32_u24_e32 v129, 0x1200, v120
	v_mul_u32_u24_e32 v130, 0x110, v118
	v_add_u32_e32 v121, v129, v130
	v_add_u32_e32 v121, 0x8000, v121
	v_lshl_add_u32 v121, v128, 4, v121
	v_mul_u32_u24_e32 v130, 0x110, v128
	v_add_u32_e32 v122, v129, v130
	v_add_u32_e32 v122, 0x8000, v122
	v_lshl_add_u32 v122, v118, 3, v122
	v_pk_add_f32 v[42:43], v[42:43], v[48:49]
	s_nop 0
	v_pk_add_f32 v[42:43], v[42:43], v[38:39]
	v_xad_u32 v38, v58, 32, v57
	v_or_b32_e32 v67, v38, v56
	v_xad_u32 v38, v58, 48, v57
	v_or_b32_e32 v68, v38, v56
	v_lshlrev_b32_e32 v38, 16, v40
	v_and_b32_e32 v39, 0xffff0000, v40
	v_pk_mul_f32 v[48:49], v[38:39], v[38:39]
	v_xad_u32 v40, v58, 64, v57
	v_mov_b32_e32 v50, v48
	v_mov_b32_e32 v51, v38
	v_mov_b32_e32 v48, v49
	v_mov_b32_e32 v49, v39
	v_or_b32_e32 v69, v40, v56
	v_xad_u32 v40, v58, s35, v57
	v_pk_add_f32 v[48:49], v[50:51], v[48:49]
	v_or_b32_e32 v70, v40, v56
	v_lshlrev_b32_e32 v40, 16, v41
	v_and_b32_e32 v41, 0xffff0000, v41
	v_pk_add_f32 v[42:43], v[48:49], v[42:43]
	v_pk_mul_f32 v[48:49], v[40:41], v[40:41]
	v_mov_b32_e32 v51, v40
	v_mov_b32_e32 v50, v48
	v_mov_b32_e32 v48, v49
	v_mov_b32_e32 v49, v41
	v_pk_add_f32 v[48:49], v[50:51], v[48:49]
	s_movk_i32 s35, 0x60
	v_pk_add_f32 v[48:49], v[48:49], v[42:43]
	v_xad_u32 v42, v58, s35, v57
	v_or_b32_e32 v71, v42, v56
	v_xad_u32 v42, v58, s14, v57
	v_or_b32_e32 v72, v42, v56
	v_lshlrev_b32_e32 v42, 16, v22
	v_and_b32_e32 v43, 0xffff0000, v22
	v_pk_mul_f32 v[50:51], v[42:43], v[42:43]
	v_xad_u32 v22, v58, s8, v57
	s_movk_i32 s35, 0x90
	v_mov_b32_e32 v52, v50
	v_mov_b32_e32 v53, v42
	v_mov_b32_e32 v50, v51
	v_mov_b32_e32 v51, v43
	v_or_b32_e32 v73, v22, v56
; DI void gmlp_unit(const Params& p, int l, int T, int g, ldsp_t smem) {
;     ...
;         float a = 0.f, b = 0.f;
; #pragma unroll
;         for (int i = 0; i < 4; ++i)
; #pragma unroll
;             for (int j = 0; j < 4; ++j) {
;                 const float lo = __uint_as_float(raw[i][j] << 16), hi = __uint_as_float(raw[i][j] & 0xffff0000u);
;                 a += lo + hi; b += lo * lo + hi * hi;
;             }
;         a += __shfl_xor(a, 1); a += __shfl_xor(a, 2);
;         b += __shfl_xor(b, 1); b += __shfl_xor(b, 2);
;         const float mean = a * (1.f / 128.f);
;         const float rstd = rsqrtf(fmaxf(b * (1.f / 128.f) - mean * mean, 0.f) + EPS);
;         const float* gn = p.gmlp_norm_g + l * 512 + g * 128 + part * 32;
	v_xad_u32 v22, v58, s35, v57
	v_pk_add_f32 v[50:51], v[52:53], v[50:51]
	v_or_b32_e32 v74, v22, v56
	v_lshlrev_b32_e32 v22, 16, v23
	v_and_b32_e32 v23, 0xffff0000, v23
	v_pk_add_f32 v[48:49], v[50:51], v[48:49]
	v_pk_mul_f32 v[50:51], v[22:23], v[22:23]
	v_mov_b32_e32 v53, v22
	v_mov_b32_e32 v52, v50
	v_mov_b32_e32 v50, v51
	v_mov_b32_e32 v51, v23
	v_pk_add_f32 v[50:51], v[52:53], v[50:51]
	s_movk_i32 s35, 0xa0
	v_pk_add_f32 v[48:49], v[50:51], v[48:49]
	v_xad_u32 v50, v58, s35, v57
	s_movk_i32 s35, 0xb0
	v_or_b32_e32 v75, v50, v56
	v_xad_u32 v50, v58, s35, v57
	v_or_b32_e32 v76, v50, v56
	v_lshlrev_b32_e32 v50, 16, v24
	v_and_b32_e32 v51, 0xffff0000, v24
	v_pk_mul_f32 v[52:53], v[50:51], v[50:51]
	v_xad_u32 v24, v58, s15, v57
	s_movk_i32 s35, 0xd0
	v_mov_b32_e32 v54, v52
	v_mov_b32_e32 v55, v50
	v_mov_b32_e32 v52, v53
	v_mov_b32_e32 v53, v51
	v_or_b32_e32 v77, v24, v56
	v_xad_u32 v24, v58, s35, v57
	v_pk_add_f32 v[52:53], v[54:55], v[52:53]
	v_or_b32_e32 v78, v24, v56
	v_lshlrev_b32_e32 v24, 16, v25
	v_and_b32_e32 v25, 0xffff0000, v25
	v_pk_add_f32 v[48:49], v[52:53], v[48:49]
	v_pk_mul_f32 v[52:53], v[24:25], v[24:25]
	v_mov_b32_e32 v55, v24
	v_mov_b32_e32 v54, v52
	v_mov_b32_e32 v52, v53
	v_mov_b32_e32 v53, v25
	v_pk_add_f32 v[52:53], v[54:55], v[52:53]
	s_movk_i32 s35, 0xe0
	v_pk_add_f32 v[48:49], v[52:53], v[48:49]
	v_xad_u32 v52, v58, s35, v57
	s_movk_i32 s35, 0xf0
	v_or_b32_e32 v79, v52, v56
	v_xad_u32 v52, v58, s35, v57
	v_or_b32_e32 v80, v52, v56
	v_lshlrev_b32_e32 v52, 16, v10
	v_and_b32_e32 v53, 0xffff0000, v10
	v_pk_mul_f32 v[54:55], v[52:53], v[52:53]
	v_mov_b32_e32 v57, v52
	v_mov_b32_e32 v56, v54
	v_mov_b32_e32 v54, v55
	v_mov_b32_e32 v55, v53
	v_pk_add_f32 v[54:55], v[56:57], v[54:55]
	s_nop 0
	v_pk_add_f32 v[48:49], v[54:55], v[48:49]
	v_lshlrev_b32_e32 v54, 16, v11
	v_and_b32_e32 v55, 0xffff0000, v11
	v_pk_mul_f32 v[10:11], v[54:55], v[54:55]
	v_mov_b32_e32 v57, v54
	v_mov_b32_e32 v56, v10
	v_mov_b32_e32 v10, v11
	v_mov_b32_e32 v11, v55
	v_pk_add_f32 v[10:11], v[56:57], v[10:11]
	s_nop 0
	v_pk_add_f32 v[10:11], v[10:11], v[48:49]
	v_lshlrev_b32_e32 v48, 16, v12
	v_and_b32_e32 v49, 0xffff0000, v12
	v_pk_mul_f32 v[56:57], v[48:49], v[48:49]
	v_mov_b32_e32 v59, v48
	v_mov_b32_e32 v58, v56
	v_mov_b32_e32 v56, v57
	v_mov_b32_e32 v57, v49
	v_pk_add_f32 v[56:57], v[58:59], v[56:57]
	s_nop 0
	v_pk_add_f32 v[10:11], v[56:57], v[10:11]
	v_lshlrev_b32_e32 v56, 16, v13
	v_and_b32_e32 v57, 0xffff0000, v13
	v_pk_mul_f32 v[12:13], v[56:57], v[56:57]
	v_mov_b32_e32 v59, v56
	v_mov_b32_e32 v58, v12
	v_mov_b32_e32 v12, v13
	v_mov_b32_e32 v13, v57
	v_pk_add_f32 v[12:13], v[58:59], v[12:13]
	v_lshlrev_b32_e32 v58, 16, v0
	v_and_b32_e32 v59, 0xffff0000, v0
	v_pk_add_f32 v[10:11], v[12:13], v[10:11]
	v_pk_mul_f32 v[12:13], v[58:59], v[58:59]
	v_mov_b32_e32 v61, v58
	v_mov_b32_e32 v60, v12
	v_mov_b32_e32 v12, v13
	v_mov_b32_e32 v13, v59
	v_pk_add_f32 v[12:13], v[60:61], v[12:13]
	v_lshlrev_b32_e32 v60, 16, v1
	v_and_b32_e32 v61, 0xffff0000, v1
	v_pk_mul_f32 v[0:1], v[60:61], v[60:61]
	v_pk_add_f32 v[10:11], v[12:13], v[10:11]
	v_mov_b32_e32 v12, v0
	v_mov_b32_e32 v13, v60
	v_mov_b32_e32 v0, v1
	v_mov_b32_e32 v1, v61
	v_pk_add_f32 v[0:1], v[12:13], v[0:1]
	s_nop 0
	v_pk_add_f32 v[0:1], v[0:1], v[10:11]
	s_nop 0
	v_pk_add_f32 v[0:1], v[30:31], v[0:1]
	s_nop 0
	v_pk_add_f32 v[0:1], v[32:33], v[0:1]
	ds_bpermute_b32 v11, v62, v1
	ds_bpermute_b32 v10, v62, v0
	s_waitcnt lgkmcnt(0)
	v_pk_add_f32 v[0:1], v[0:1], v[10:11]
	ds_bpermute_b32 v11, v63, v1
	ds_bpermute_b32 v10, v63, v0
	s_waitcnt lgkmcnt(0)
	v_pk_add_f32 v[0:1], v[0:1], v[10:11]
	s_nop 0
	v_pk_mul_f32 v[30:31], v[0:1], s[36:37] op_sel_hi:[1,0]
	v_readlane_b32 s36, v253, 3
	v_fma_f32 v0, -v31, v31, v30
	v_max_f32_e32 v0, 0, v0
	v_add_f32_e32 v0, 0x358637bd, v0
	v_cmp_gt_f32_e32 vcc, s92, v0
	v_mul_f32_e32 v1, 0x4b800000, v0
	v_readlane_b32 s44, v253, 11
	v_cndmask_b32_e32 v0, v0, v1, vcc
	v_rsq_f32_e32 v0, v0
	v_readlane_b32 s45, v253, 12
	v_readlane_b32 s37, v253, 4
	v_readlane_b32 s38, v253, 5
	v_mul_f32_e32 v1, 0x45800000, v0
	v_cndmask_b32_e32 v32, v0, v1, vcc
	v_pk_add_f32 v[0:1], v[34:35], v[30:31] op_sel:[0,1] neg_lo:[0,1] neg_hi:[0,1]
	v_bfi_b32 v34, -16, v47, v46
	v_pk_mul_f32 v[0:1], v[0:1], v[32:33] op_sel_hi:[1,0]
	v_ashrrev_i32_e32 v35, 31, v34
	s_waitcnt vmcnt(13)
; #define LDSP __attribute__((address_space(3)))
; DI unsigned pk2(float a, float b) { f32x2 v = {a, b}; bf2_t r = __builtin_convertvector(v, bf2_t); return __builtin_bit_cast(unsigned, r); }
; DI void gmlp_unit(const Params& p, int l, int T, int g, ldsp_t smem) {
;     ...
;         const float* gn = p.gmlp_norm_g + l * 512 + g * 128 + part * 32;
; #pragma unroll
;         for (int i = 0; i < 4; ++i)
; #pragma unroll
;             for (int j = 0; j < 4; ++j) {
;                 const int c0 = part * 32 + i * 8 + j * 2;
;                 const float lo = __uint_as_float(raw[i][j] << 16), hi = __uint_as_float(raw[i][j] & 0xffff0000u);
;                 const unsigned w = pk2((lo - mean) * rstd * gn[i * 8 + j * 2], (hi - mean) * rstd * gn[i * 8 + j * 2 + 1]);
;                 *(LDSP bf16_t*)(smem + c0 * 256 + (((q >> 3) ^ (c0 & 15)) << 4) + (q & 7) * 2) = (bf16_t)(w & 0xffffu);
;                 *(LDSP bf16_t*)(smem + (c0 + 1) * 256 + (((q >> 3) ^ ((c0 + 1) & 15)) << 4) + (q & 7) * 2) = (bf16_t)(w >> 16);
;             }
;     }
;     __syncthreads();
	v_pk_mul_f32 v[0:1], v[18:19], v[0:1]
	v_readlane_b32 s39, v253, 6
	v_cvt_pk_bf16_f32 v0, v0, v1
	ds_write_b16 v65, v0
	ds_write_b16_d16_hi v66, v0 offset:256
	v_pk_add_f32 v[0:1], v[36:37], v[30:31] op_sel:[0,1] neg_lo:[0,1] neg_hi:[0,1]
	v_readlane_b32 s40, v253, 7
	v_pk_mul_f32 v[0:1], v[0:1], v[32:33] op_sel_hi:[1,0]
	v_readlane_b32 s41, v253, 8
	v_pk_mul_f32 v[0:1], v[20:21], v[0:1]
	v_readlane_b32 s42, v253, 9
	v_cvt_pk_bf16_f32 v0, v0, v1
	ds_write_b16 v67, v0 offset:512
	ds_write_b16_d16_hi v68, v0 offset:768
	v_pk_add_f32 v[0:1], v[38:39], v[30:31] op_sel:[0,1] neg_lo:[0,1] neg_hi:[0,1]
	v_readlane_b32 s43, v253, 10
	v_pk_mul_f32 v[0:1], v[0:1], v[32:33] op_sel_hi:[1,0]
	v_readlane_b32 s46, v253, 13
	v_pk_mul_f32 v[0:1], v[14:15], v[0:1]
	v_readlane_b32 s47, v253, 14
	v_cvt_pk_bf16_f32 v0, v0, v1
	ds_write_b16 v69, v0 offset:1024
	ds_write_b16_d16_hi v70, v0 offset:1280
	v_pk_add_f32 v[0:1], v[40:41], v[30:31] op_sel:[0,1] neg_lo:[0,1] neg_hi:[0,1]
	v_readlane_b32 s48, v253, 15
	v_pk_mul_f32 v[0:1], v[0:1], v[32:33] op_sel_hi:[1,0]
	v_readlane_b32 s49, v253, 16
	v_pk_mul_f32 v[0:1], v[16:17], v[0:1]
	v_readlane_b32 s50, v253, 17
	v_cvt_pk_bf16_f32 v0, v0, v1
	ds_write_b16 v71, v0 offset:1536
	ds_write_b16_d16_hi v72, v0 offset:1792
	v_pk_add_f32 v[0:1], v[42:43], v[30:31] op_sel:[0,1] neg_lo:[0,1] neg_hi:[0,1]
	v_readlane_b32 s51, v253, 18
	v_pk_mul_f32 v[0:1], v[0:1], v[32:33] op_sel_hi:[1,0]
	s_nop 0
	v_pk_mul_f32 v[0:1], v[6:7], v[0:1]
	s_nop 0
	v_cvt_pk_bf16_f32 v0, v0, v1
	ds_write_b16 v73, v0 offset:2048
	ds_write_b16_d16_hi v74, v0 offset:2304
	v_pk_add_f32 v[0:1], v[22:23], v[30:31] op_sel:[0,1] neg_lo:[0,1] neg_hi:[0,1]
	s_nop 0
	v_pk_mul_f32 v[0:1], v[0:1], v[32:33] op_sel_hi:[1,0]
	s_nop 0
	v_pk_mul_f32 v[0:1], v[8:9], v[0:1]
	s_nop 0
	v_cvt_pk_bf16_f32 v0, v0, v1
	ds_write_b16 v75, v0 offset:2560
	ds_write_b16_d16_hi v76, v0 offset:2816
	v_pk_add_f32 v[0:1], v[50:51], v[30:31] op_sel:[0,1] neg_lo:[0,1] neg_hi:[0,1]
	s_nop 0
	v_pk_mul_f32 v[0:1], v[0:1], v[32:33] op_sel_hi:[1,0]
	s_nop 0
	v_pk_mul_f32 v[0:1], v[0:1], v[2:3]
	s_nop 0
	v_cvt_pk_bf16_f32 v0, v0, v1
	ds_write_b16 v77, v0 offset:3072
	ds_write_b16_d16_hi v78, v0 offset:3328
	v_pk_add_f32 v[0:1], v[24:25], v[30:31] op_sel:[0,1] neg_lo:[0,1] neg_hi:[0,1]
	s_nop 0
	v_pk_mul_f32 v[0:1], v[0:1], v[32:33] op_sel_hi:[1,0]
	s_nop 0
	v_pk_mul_f32 v[0:1], v[0:1], v[4:5]
	s_nop 0
	v_cvt_pk_bf16_f32 v0, v0, v1
	ds_write_b16 v79, v0 offset:3584
	ds_write_b16_d16_hi v80, v0 offset:3840
	v_pk_add_f32 v[0:1], v[52:53], v[30:31] op_sel:[0,1] neg_lo:[0,1] neg_hi:[0,1]
	s_nop 0
	v_pk_mul_f32 v[16:17], v[0:1], v[32:33] op_sel_hi:[1,0]
	s_nop 0
	s_nop 0
	s_nop 0
	s_nop 0
	s_or_b32 s4, s34, s7
	s_ashr_i32 s5, s4, 31
	s_lshl_b64 s[4:5], s[4:5], 7
	s_waitcnt vmcnt(9)
	v_pk_mul_f32 v[12:13], v[16:17], v[96:97]
	s_nop 0
	v_cvt_pk_bf16_f32 v12, v12, v13
	ds_write_b16 v65, v12 offset:4096
	ds_write_b16_d16_hi v66, v12 offset:4352
	v_pk_add_f32 v[12:13], v[54:55], v[30:31] op_sel:[0,1] neg_lo:[0,1] neg_hi:[0,1]
	s_nop 0
	v_pk_mul_f32 v[12:13], v[12:13], v[32:33] op_sel_hi:[1,0]
	s_nop 0
	v_pk_mul_f32 v[12:13], v[12:13], v[98:99]
	s_nop 0
	v_cvt_pk_bf16_f32 v12, v12, v13
	ds_write_b16 v67, v12 offset:4608
	ds_write_b16_d16_hi v68, v12 offset:4864
	v_pk_add_f32 v[12:13], v[48:49], v[30:31] op_sel:[0,1] neg_lo:[0,1] neg_hi:[0,1]
	s_nop 0
	v_pk_mul_f32 v[12:13], v[12:13], v[32:33] op_sel_hi:[1,0]
	s_nop 0
	v_pk_mul_f32 v[8:9], v[12:13], v[92:93]
	s_nop 0
	v_cvt_pk_bf16_f32 v8, v8, v9
	ds_write_b16 v69, v8 offset:5120
	ds_write_b16_d16_hi v70, v8 offset:5376
	v_pk_add_f32 v[8:9], v[56:57], v[30:31] op_sel:[0,1] neg_lo:[0,1] neg_hi:[0,1]
	s_nop 0
	v_pk_mul_f32 v[8:9], v[8:9], v[32:33] op_sel_hi:[1,0]
	s_nop 0
	v_pk_mul_f32 v[8:9], v[8:9], v[94:95]
	s_nop 0
	v_cvt_pk_bf16_f32 v8, v8, v9
	ds_write_b16 v71, v8 offset:5632
	ds_write_b16_d16_hi v72, v8 offset:5888
	v_pk_add_f32 v[8:9], v[58:59], v[30:31] op_sel:[0,1] neg_lo:[0,1] neg_hi:[0,1]
	s_nop 0
	v_pk_mul_f32 v[8:9], v[8:9], v[32:33] op_sel_hi:[1,0]
	s_nop 0
	v_pk_mul_f32 v[4:5], v[8:9], v[88:89]
	s_nop 0
	v_cvt_pk_bf16_f32 v4, v4, v5
	ds_write_b16 v73, v4 offset:6144
	ds_write_b16_d16_hi v74, v4 offset:6400
	v_pk_add_f32 v[4:5], v[60:61], v[30:31] op_sel:[0,1] neg_lo:[0,1] neg_hi:[0,1]
	s_nop 0
	v_pk_mul_f32 v[4:5], v[4:5], v[32:33] op_sel_hi:[1,0]
	s_nop 0
	v_pk_mul_f32 v[4:5], v[4:5], v[90:91]
	s_nop 0
	v_cvt_pk_bf16_f32 v4, v4, v5
	ds_write_b16 v75, v4 offset:6656
	ds_write_b16_d16_hi v76, v4 offset:6912
	v_pk_add_f32 v[4:5], v[28:29], v[30:31] op_sel:[0,1] neg_lo:[0,1] neg_hi:[0,1]
	s_nop 0
	v_pk_mul_f32 v[4:5], v[4:5], v[32:33] op_sel_hi:[1,0]
	s_nop 0
	v_pk_mul_f32 v[0:1], v[4:5], v[84:85]
	v_bfe_u32 v4, v46, 4, 2
	v_cvt_pk_bf16_f32 v0, v0, v1
	ds_write_b16 v77, v0 offset:7168
	ds_write_b16_d16_hi v78, v0 offset:7424
	v_pk_add_f32 v[0:1], v[26:27], v[30:31] op_sel:[0,1] neg_lo:[0,1] neg_hi:[0,1]
	v_lshlrev_b32_e32 v5, 8, v45
	v_pk_mul_f32 v[0:1], v[0:1], v[32:33] op_sel_hi:[1,0]
	v_lshl_add_u64 v[32:33], s[4:5], 0, v[34:35]
	v_pk_mul_f32 v[0:1], v[0:1], v[86:87]
	v_lshlrev_b32_e32 v2, 4, v4
	v_cvt_pk_bf16_f32 v0, v0, v1
	ds_write_b16 v79, v0 offset:7680
	ds_write_b16_d16_hi v80, v0 offset:7936
	v_lshlrev_b64 v[0:1], 8, v[32:33]
	v_lshl_add_u64 v[0:1], s[64:65], 0, v[0:1]
	v_mov_b32_e32 v3, v193
	v_lshl_add_u64 v[6:7], v[0:1], 0, v[2:3]
	s_waitcnt lgkmcnt(0)
	s_barrier
; #define LDSP __attribute__((address_space(3)))
; DI void gmlp_unit(const Params& p, int l, int T, int g, ldsp_t smem) {
;     ...
;     const int prow = wid * 16 + fr;
;     const bf16_t* wsp = p.ws_bf + ((size_t)(l * 4 + g) * 128 + prow) * 128 + fq * 8;
;     bf16x8 a[4];
; #pragma unroll
;     for (int ks = 0; ks < 4; ++ks) a[ks] = *(const bf16x8*)(wsp + ks * 32);
;     f32x4 acc[8];
; #pragma unroll
;     for (int n = 0; n < 8; ++n) {
;         acc[n] = (f32x4){0.f, 0.f, 0.f, 0.f};
;         const int c = n * 16 + fr;
; #pragma unroll
;         for (int ks = 0; ks < 4; ++ks) {
;             const bf16x8 bq = *(const LDSP bf16x8*)(smem + c * 256 + (((ks * 4 + fq) ^ (c & 15)) << 4));
;             acc[n] = __builtin_amdgcn_mfma_f32_16x16x32_bf16(bq, a[ks], acc[n], 0, 0, 0);
;         }
;     }
;     const float bs = p.b_spatial[(size_t)(l * 4 + g) * 128 + prow];
	s_nop 0
	s_nop 0
	s_nop 0
	s_nop 0
	v_bitop3_b32 v6, v44, v45, 3 bitop3:0x6c
	v_lshl_or_b32 v35, v6, 4, v5
	ds_read_b128 v[6:9], v35
	v_bitop3_b32 v10, v4, v45, 4 bitop3:0x36
	v_lshl_or_b32 v44, v10, 4, v5
	ds_read_b128 v[10:13], v44
	s_waitcnt vmcnt(8) lgkmcnt(1)
	v_mfma_f32_16x16x32_bf16 v[6:9], v[6:9], v[140:143], 0
	v_lshlrev_b32_e32 v192, 3, v4
	ds_read_b128 v[50:53], v44 offset:24576
	v_add_u32_e32 v34, s31, v34
	s_waitcnt vmcnt(7) lgkmcnt(1)
	v_mfma_f32_16x16x32_bf16 v[6:9], v[10:13], v[144:147], v[6:9]
	v_bitop3_b32 v10, v4, v45, 8 bitop3:0x36
	v_lshl_or_b32 v54, v10, 4, v5
	ds_read_b128 v[10:13], v54
	v_bitop3_b32 v4, v4, v45, 12 bitop3:0x36
	v_lshl_or_b32 v45, v4, 4, v5
	s_waitcnt vmcnt(5) lgkmcnt(0)
	v_mfma_f32_16x16x32_bf16 v[6:9], v[10:13], v[148:151], v[6:9]
	ds_read_b128 v[10:13], v45
	v_lshl_add_u64 v[32:33], v[32:33], 2, s[44:45]
	s_nop 0
	s_waitcnt vmcnt(5) lgkmcnt(0)
	v_mfma_f32_16x16x32_bf16 v[28:31], v[10:13], v[152:155], v[6:9]
	s_nop 2
	ds_read_b128 v[4:7], v35 offset:4096
	ds_read_b128 v[8:11], v44 offset:4096
	s_waitcnt vmcnt(4)
	v_mov_b32_e32 v32, v156
	s_nop 1
	v_pk_add_f32 v[28:29], v[28:29], v[32:33] op_sel_hi:[1,0]
	s_waitcnt lgkmcnt(1)
	v_mfma_f32_16x16x32_bf16 v[4:7], v[4:7], v[140:143], 0
	v_add_f32_e64 v30, v30, v32
	v_add_f32_e64 v31, v31, v32
	s_waitcnt lgkmcnt(0)
	v_mfma_f32_16x16x32_bf16 v[4:7], v[8:11], v[144:147], v[4:7]
	ds_read_b128 v[8:11], v54 offset:4096
	s_waitcnt lgkmcnt(0)
	v_mfma_f32_16x16x32_bf16 v[4:7], v[8:11], v[148:151], v[4:7]
	ds_read_b128 v[8:11], v45 offset:4096
	s_waitcnt lgkmcnt(0)
	v_mfma_f32_16x16x32_bf16 v[24:27], v[8:11], v[152:155], v[4:7]
	s_nop 4
	ds_read_b128 v[4:7], v35 offset:8192
	ds_read_b128 v[8:11], v44 offset:8192
	s_nop 0
	v_pk_add_f32 v[24:25], v[24:25], v[32:33] op_sel_hi:[1,0]
	s_waitcnt lgkmcnt(1)
	v_mfma_f32_16x16x32_bf16 v[4:7], v[4:7], v[140:143], 0
	v_add_f32_e64 v26, v26, v32
	v_add_f32_e64 v27, v27, v32
	s_waitcnt lgkmcnt(0)
	v_mfma_f32_16x16x32_bf16 v[4:7], v[8:11], v[144:147], v[4:7]
	ds_read_b128 v[8:11], v54 offset:8192
	s_waitcnt lgkmcnt(0)
	v_mfma_f32_16x16x32_bf16 v[4:7], v[8:11], v[148:151], v[4:7]
	ds_read_b128 v[8:11], v45 offset:8192
	s_waitcnt lgkmcnt(0)
	v_mfma_f32_16x16x32_bf16 v[20:23], v[8:11], v[152:155], v[4:7]
	s_nop 4
	ds_read_b128 v[4:7], v35 offset:12288
	ds_read_b128 v[8:11], v44 offset:12288
	s_nop 0
	v_pk_add_f32 v[20:21], v[20:21], v[32:33] op_sel_hi:[1,0]
	s_waitcnt lgkmcnt(1)
	v_mfma_f32_16x16x32_bf16 v[4:7], v[4:7], v[140:143], 0
	v_add_f32_e64 v22, v22, v32
	v_add_f32_e64 v23, v23, v32
	s_waitcnt lgkmcnt(0)
	v_mfma_f32_16x16x32_bf16 v[4:7], v[8:11], v[144:147], v[4:7]
	ds_read_b128 v[8:11], v54 offset:12288
	s_waitcnt lgkmcnt(0)
	v_mfma_f32_16x16x32_bf16 v[4:7], v[8:11], v[148:151], v[4:7]
	ds_read_b128 v[8:11], v45 offset:12288
	s_waitcnt lgkmcnt(0)
	v_mfma_f32_16x16x32_bf16 v[16:19], v[8:11], v[152:155], v[4:7]
	s_nop 4
	ds_read_b128 v[4:7], v35 offset:16384
	ds_read_b128 v[8:11], v44 offset:16384
	s_nop 0
	v_pk_add_f32 v[16:17], v[16:17], v[32:33] op_sel_hi:[1,0]
	s_waitcnt lgkmcnt(1)
	v_mfma_f32_16x16x32_bf16 v[4:7], v[4:7], v[140:143], 0
	v_add_f32_e64 v18, v18, v32
	v_add_f32_e64 v19, v19, v32
	s_waitcnt lgkmcnt(0)
	v_mfma_f32_16x16x32_bf16 v[4:7], v[8:11], v[144:147], v[4:7]
	ds_read_b128 v[8:11], v54 offset:16384
	s_waitcnt lgkmcnt(0)
	v_mfma_f32_16x16x32_bf16 v[4:7], v[8:11], v[148:151], v[4:7]
	ds_read_b128 v[8:11], v45 offset:16384
	s_waitcnt lgkmcnt(0)
	v_mfma_f32_16x16x32_bf16 v[12:15], v[8:11], v[152:155], v[4:7]
	s_nop 4
	ds_read_b128 v[4:7], v35 offset:20480
	ds_read_b128 v[8:11], v44 offset:20480
	s_nop 0
	v_pk_add_f32 v[12:13], v[12:13], v[32:33] op_sel_hi:[1,0]
	s_waitcnt lgkmcnt(1)
	v_mfma_f32_16x16x32_bf16 v[4:7], v[4:7], v[140:143], 0
	v_add_f32_e64 v14, v14, v32
	v_add_f32_e64 v15, v15, v32
	s_waitcnt lgkmcnt(0)
	v_mfma_f32_16x16x32_bf16 v[4:7], v[8:11], v[144:147], v[4:7]
	ds_read_b128 v[8:11], v54 offset:20480
	s_waitcnt lgkmcnt(0)
	v_mfma_f32_16x16x32_bf16 v[4:7], v[8:11], v[148:151], v[4:7]
	ds_read_b128 v[8:11], v45 offset:20480
	s_waitcnt lgkmcnt(0)
	v_mfma_f32_16x16x32_bf16 v[8:11], v[8:11], v[152:155], v[4:7]
	s_nop 4
	ds_read_b128 v[4:7], v35 offset:24576
	s_nop 1
	v_pk_add_f32 v[8:9], v[8:9], v[32:33] op_sel_hi:[1,0]
	s_waitcnt lgkmcnt(0)
	v_mfma_f32_16x16x32_bf16 v[4:7], v[4:7], v[140:143], 0
	v_add_f32_e64 v10, v10, v32
	v_add_f32_e64 v11, v11, v32
	v_mfma_f32_16x16x32_bf16 v[4:7], v[50:53], v[144:147], v[4:7]
	ds_read_b128 v[50:53], v54 offset:24576
	s_waitcnt lgkmcnt(0)
	v_mfma_f32_16x16x32_bf16 v[4:7], v[50:53], v[148:151], v[4:7]
	ds_read_b128 v[50:53], v45 offset:24576
	s_waitcnt lgkmcnt(0)
	v_mfma_f32_16x16x32_bf16 v[4:7], v[50:53], v[152:155], v[4:7]
	ds_read_b128 v[50:53], v35 offset:28672
	v_ashrrev_i32_e32 v35, 31, v34
	s_nop 5
	v_pk_add_f32 v[4:5], v[4:5], v[32:33] op_sel_hi:[1,0]
	s_waitcnt lgkmcnt(0)
; DI unsigned pk2(float a, float b) { f32x2 v = {a, b}; bf2_t r = __builtin_convertvector(v, bf2_t); return __builtin_bit_cast(unsigned, r); }
; DI void gmlp_unit(const Params& p, int l, int T, int g, ldsp_t smem) {
;     ...
;     const float bs = p.b_spatial[(size_t)(l * 4 + g) * 128 + prow];
;     const int row = T * 128 + prow;
;     const bf16_t* up = p.U + (size_t)row * 1024 + g * 128 + fq * 4;
;     bf16_t* mp = p.MIX + (size_t)row * DM + 512 + g * 128 + fq * 4;
; #pragma unroll
;     for (int n = 0; n < 8; ++n) {
;         const u32x2 uu = *(const u32x2*)(up + n * 16);
;         const float u0 = __uint_as_float(uu[0] << 16), u1 = __uint_as_float(uu[0] & 0xffff0000u), u2 = __uint_as_float(uu[1] << 16), u3 = __uint_as_float(uu[1] & 0xffff0000u);
;         u32x2 w; w[0] = pk2((acc[n][0] + bs) * u0, (acc[n][1] + bs) * u1); w[1] = pk2((acc[n][2] + bs) * u2, (acc[n][3] + bs) * u3);
;         *(u32x2*)(mp + n * 16) = w;
;     }
;     __syncthreads();
	v_mfma_f32_16x16x32_bf16 v[0:3], v[50:53], v[140:143], 0
	ds_read_b128 v[50:53], v44 offset:28672
	v_pk_add_f32 v[6:7], v[6:7], v[32:33] op_sel_hi:[1,0]
	s_waitcnt lgkmcnt(0)
	v_mfma_f32_16x16x32_bf16 v[0:3], v[50:53], v[144:147], v[0:3]
	ds_read_b128 v[36:39], v54 offset:28672
	s_waitcnt lgkmcnt(0)
	v_mfma_f32_16x16x32_bf16 v[0:3], v[36:39], v[148:151], v[0:3]
	ds_read_b128 v[36:39], v45 offset:28672
	s_waitcnt lgkmcnt(0)
	v_mfma_f32_16x16x32_bf16 v[0:3], v[36:39], v[152:155], v[0:3]
	v_lshlrev_b64 v[36:37], 11, v[34:35]
	v_lshl_add_u64 v[34:35], s[16:17], 0, v[36:37]
	v_lshl_add_u64 v[34:35], v[34:35], 0, s[98:99]
	v_lshl_add_u64 v[34:35], v[34:35], 0, v[192:193]
	s_nop 0
	v_lshl_add_u64 v[36:37], s[18:19], 0, v[36:37]
	v_lshl_add_u64 v[36:37], v[36:37], 0, s[98:99]
	v_lshl_add_u64 v[36:37], v[36:37], 0, v[192:193]
	v_pk_add_f32 v[0:1], v[0:1], v[32:33] op_sel_hi:[1,0]
	v_pk_add_f32 v[2:3], v[2:3], v[32:33] op_sel_hi:[1,0]
	s_waitcnt vmcnt(0)
	ds_write_b128 v121, v[168:171]
	ds_write_b128 v121, v[172:175] offset:1088
	ds_write_b128 v121, v[176:179] offset:2176
	ds_write_b128 v121, v[180:183] offset:3264
	ds_read_b64 v[100:101], v122
	ds_read_b64 v[102:103], v122 offset:32
	ds_read_b64 v[104:105], v122 offset:64
	ds_read_b64 v[106:107], v122 offset:96
	ds_read_b64 v[108:109], v122 offset:128
	ds_read_b64 v[110:111], v122 offset:160
	ds_read_b64 v[112:113], v122 offset:192
	ds_read_b64 v[114:115], v122 offset:224
	s_waitcnt lgkmcnt(0)
	v_lshlrev_b32_e32 v160, 16, v100
	v_and_b32_e32 v161, 0xffff0000, v100
	v_lshlrev_b32_e32 v162, 16, v101
	v_and_b32_e32 v163, 0xffff0000, v101
	v_pk_mul_f32 v[28:29], v[28:29], v[160:161]
	v_pk_mul_f32 v[30:31], v[30:31], v[162:163]
	v_cvt_pk_bf16_f32 v28, v28, v29
	v_cvt_pk_bf16_f32 v29, v30, v31
	ds_write_b64 v122, v[28:29]
	v_lshlrev_b32_e32 v160, 16, v102
	v_and_b32_e32 v161, 0xffff0000, v102
	v_lshlrev_b32_e32 v162, 16, v103
	v_and_b32_e32 v163, 0xffff0000, v103
	v_pk_mul_f32 v[24:25], v[24:25], v[160:161]
	v_pk_mul_f32 v[26:27], v[26:27], v[162:163]
	v_cvt_pk_bf16_f32 v24, v24, v25
	v_cvt_pk_bf16_f32 v25, v26, v27
	ds_write_b64 v122, v[24:25] offset:32
	v_lshlrev_b32_e32 v160, 16, v104
	v_and_b32_e32 v161, 0xffff0000, v104
	v_lshlrev_b32_e32 v162, 16, v105
	v_and_b32_e32 v163, 0xffff0000, v105
	v_pk_mul_f32 v[20:21], v[20:21], v[160:161]
	v_pk_mul_f32 v[22:23], v[22:23], v[162:163]
	v_cvt_pk_bf16_f32 v20, v20, v21
	v_cvt_pk_bf16_f32 v21, v22, v23
	ds_write_b64 v122, v[20:21] offset:64
	v_lshlrev_b32_e32 v160, 16, v106
	v_and_b32_e32 v161, 0xffff0000, v106
	v_lshlrev_b32_e32 v162, 16, v107
	v_and_b32_e32 v163, 0xffff0000, v107
	v_pk_mul_f32 v[16:17], v[16:17], v[160:161]
	v_pk_mul_f32 v[18:19], v[18:19], v[162:163]
	v_cvt_pk_bf16_f32 v16, v16, v17
	v_cvt_pk_bf16_f32 v17, v18, v19
	ds_write_b64 v122, v[16:17] offset:96
	v_lshlrev_b32_e32 v160, 16, v108
	v_and_b32_e32 v161, 0xffff0000, v108
	v_lshlrev_b32_e32 v162, 16, v109
	v_and_b32_e32 v163, 0xffff0000, v109
	v_pk_mul_f32 v[12:13], v[12:13], v[160:161]
	v_pk_mul_f32 v[14:15], v[14:15], v[162:163]
	v_cvt_pk_bf16_f32 v12, v12, v13
	v_cvt_pk_bf16_f32 v13, v14, v15
	ds_write_b64 v122, v[12:13] offset:128
	v_lshlrev_b32_e32 v160, 16, v110
	v_and_b32_e32 v161, 0xffff0000, v110
	v_lshlrev_b32_e32 v162, 16, v111
	v_and_b32_e32 v163, 0xffff0000, v111
	v_pk_mul_f32 v[8:9], v[8:9], v[160:161]
	v_pk_mul_f32 v[10:11], v[10:11], v[162:163]
	v_cvt_pk_bf16_f32 v8, v8, v9
	v_cvt_pk_bf16_f32 v9, v10, v11
	ds_write_b64 v122, v[8:9] offset:160
	v_lshlrev_b32_e32 v160, 16, v112
	v_and_b32_e32 v161, 0xffff0000, v112
	v_lshlrev_b32_e32 v162, 16, v113
	v_and_b32_e32 v163, 0xffff0000, v113
	v_pk_mul_f32 v[4:5], v[4:5], v[160:161]
	v_pk_mul_f32 v[6:7], v[6:7], v[162:163]
	v_cvt_pk_bf16_f32 v4, v4, v5
	v_cvt_pk_bf16_f32 v5, v6, v7
	ds_write_b64 v122, v[4:5] offset:192
	v_lshlrev_b32_e32 v160, 16, v114
	v_and_b32_e32 v161, 0xffff0000, v114
	v_lshlrev_b32_e32 v162, 16, v115
	v_and_b32_e32 v163, 0xffff0000, v115
	v_pk_mul_f32 v[0:1], v[0:1], v[160:161]
	v_pk_mul_f32 v[2:3], v[2:3], v[162:163]
	v_cvt_pk_bf16_f32 v0, v0, v1
	v_cvt_pk_bf16_f32 v1, v2, v3
	ds_write_b64 v122, v[0:1] offset:224
	ds_read_b128 v[204:207], v121
	ds_read_b128 v[210:213], v121 offset:1088
	ds_read_b128 v[214:217], v121 offset:2176
	ds_read_b128 v[220:223], v121 offset:3264
	s_waitcnt lgkmcnt(0)
	global_store_dwordx4 v124, v[204:207], s[18:19] offset:1024
	global_store_dwordx4 v125, v[210:213], s[18:19] offset:1024
	global_store_dwordx4 v126, v[214:217], s[18:19] offset:1024
	global_store_dwordx4 v127, v[220:223], s[18:19] offset:1024
	s_barrier
	s_load_dword s4, s[88:89], 0x0
	s_waitcnt lgkmcnt(0)
	s_add_i32 s11, s4, s11
	s_cmp_ge_i32 s11, s6
	s_cbranch_scc0 .LBB0_174
